# GEMM K-loops: barrier one MFMA group earlier (group 12) with the A-first DMA order
# speedup vs baseline: 1.0083x; 1.0040x over previous
.LBB0_203:
	ds_read_b128 v[226:229], v157
	ds_read_b128 v[230:233], v158
	ds_read_b128 v[234:237], v159
	s_waitcnt lgkmcnt(5)
	v_mfma_f32_16x16x32_bf16 v[124:127], v[214:217], v[174:177], v[124:127]
	v_mfma_f32_16x16x32_bf16 v[120:123], v[214:217], v[178:181], v[120:123]
	v_mfma_f32_16x16x32_bf16 v[116:119], v[214:217], v[182:185], v[116:119]
	v_mfma_f32_16x16x32_bf16 v[112:115], v[214:217], v[186:189], v[112:115]
	ds_read_b128 v[238:241], v160
	s_waitcnt lgkmcnt(5)
	v_mfma_f32_16x16x32_bf16 v[108:111], v[218:221], v[174:177], v[108:111]
	v_mfma_f32_16x16x32_bf16 v[104:107], v[218:221], v[178:181], v[104:107]
	v_mfma_f32_16x16x32_bf16 v[100:103], v[218:221], v[182:185], v[100:103]
	v_mfma_f32_16x16x32_bf16 v[96:99], v[218:221], v[186:189], v[96:99]
	ds_read_b128 v[242:245], v161
	ds_read_b128 v[190:193], v153 offset:33792
	s_waitcnt lgkmcnt(6)
	v_mfma_f32_16x16x32_bf16 v[92:95], v[222:225], v[174:177], v[92:95]
	v_mfma_f32_16x16x32_bf16 v[88:91], v[222:225], v[178:181], v[88:91]
	v_mfma_f32_16x16x32_bf16 v[84:87], v[222:225], v[182:185], v[84:87]
	v_mfma_f32_16x16x32_bf16 v[80:83], v[222:225], v[186:189], v[80:83]
	ds_read_b128 v[214:217], v154 offset:1024
	ds_read_b128 v[194:197], v153 offset:35840
	s_waitcnt lgkmcnt(7)
	v_mfma_f32_16x16x32_bf16 v[76:79], v[226:229], v[174:177], v[76:79]
	v_mfma_f32_16x16x32_bf16 v[72:75], v[226:229], v[178:181], v[72:75]
	v_mfma_f32_16x16x32_bf16 v[68:71], v[226:229], v[182:185], v[68:71]
	v_mfma_f32_16x16x32_bf16 v[64:67], v[226:229], v[186:189], v[64:67]
	ds_read_b128 v[218:221], v155 offset:1024
	ds_read_b128 v[198:201], v153 offset:37888
	s_waitcnt lgkmcnt(8)
	v_mfma_f32_16x16x32_bf16 v[60:63], v[230:233], v[174:177], v[60:63]
	v_mfma_f32_16x16x32_bf16 v[56:59], v[230:233], v[178:181], v[56:59]
	v_mfma_f32_16x16x32_bf16 v[52:55], v[230:233], v[182:185], v[52:55]
	v_mfma_f32_16x16x32_bf16 v[48:51], v[230:233], v[186:189], v[48:51]
	ds_read_b128 v[222:225], v156 offset:1024
	ds_read_b128 v[210:213], v153 offset:39936
	s_waitcnt lgkmcnt(9)
	v_mfma_f32_16x16x32_bf16 v[44:47], v[234:237], v[174:177], v[44:47]
	v_mfma_f32_16x16x32_bf16 v[40:43], v[234:237], v[178:181], v[40:43]
	v_mfma_f32_16x16x32_bf16 v[36:39], v[234:237], v[182:185], v[36:39]
	v_mfma_f32_16x16x32_bf16 v[32:35], v[234:237], v[186:189], v[32:35]
	ds_read_b128 v[226:229], v157 offset:1024
	s_waitcnt lgkmcnt(9)
	v_mfma_f32_16x16x32_bf16 v[28:31], v[238:241], v[174:177], v[28:31]
	v_mfma_f32_16x16x32_bf16 v[24:27], v[238:241], v[178:181], v[24:27]
	v_mfma_f32_16x16x32_bf16 v[20:23], v[238:241], v[182:185], v[20:23]
	v_mfma_f32_16x16x32_bf16 v[16:19], v[238:241], v[186:189], v[16:19]
	ds_read_b128 v[230:233], v158 offset:1024
	s_waitcnt lgkmcnt(9)
	v_mfma_f32_16x16x32_bf16 v[12:15], v[242:245], v[174:177], v[12:15]
	v_mfma_f32_16x16x32_bf16 v[8:11], v[242:245], v[178:181], v[8:11]
	v_mfma_f32_16x16x32_bf16 v[4:7], v[242:245], v[182:185], v[4:7]
	v_mfma_f32_16x16x32_bf16 v[0:3], v[242:245], v[186:189], v[0:3]
	ds_read_b128 v[234:237], v159 offset:1024
	s_waitcnt lgkmcnt(3)
	v_mfma_f32_16x16x32_bf16 v[124:127], v[214:217], v[190:193], v[124:127]
	v_mfma_f32_16x16x32_bf16 v[120:123], v[214:217], v[194:197], v[120:123]
	v_mfma_f32_16x16x32_bf16 v[116:119], v[214:217], v[198:201], v[116:119]
	v_mfma_f32_16x16x32_bf16 v[112:115], v[214:217], v[210:213], v[112:115]
	ds_read_b128 v[238:241], v160 offset:1024
	v_mfma_f32_16x16x32_bf16 v[108:111], v[218:221], v[190:193], v[108:111]
	v_mfma_f32_16x16x32_bf16 v[104:107], v[218:221], v[194:197], v[104:107]
	v_mfma_f32_16x16x32_bf16 v[100:103], v[218:221], v[198:201], v[100:103]
	v_mfma_f32_16x16x32_bf16 v[96:99], v[218:221], v[210:213], v[96:99]
	ds_read_b128 v[242:245], v161 offset:1024
	v_mfma_f32_16x16x32_bf16 v[92:95], v[222:225], v[190:193], v[92:95]
	v_mfma_f32_16x16x32_bf16 v[88:91], v[222:225], v[194:197], v[88:91]
	v_mfma_f32_16x16x32_bf16 v[84:87], v[222:225], v[198:201], v[84:87]
	v_mfma_f32_16x16x32_bf16 v[80:83], v[222:225], v[210:213], v[80:83]
	s_waitcnt lgkmcnt(4)
	v_mfma_f32_16x16x32_bf16 v[76:79], v[226:229], v[190:193], v[76:79]
	v_mfma_f32_16x16x32_bf16 v[72:75], v[226:229], v[194:197], v[72:75]
	v_mfma_f32_16x16x32_bf16 v[68:71], v[226:229], v[198:201], v[68:71]
	v_mfma_f32_16x16x32_bf16 v[64:67], v[226:229], v[210:213], v[64:67]
	s_waitcnt lgkmcnt(0)
	s_waitcnt vmcnt(0)
	s_barrier
	ds_read_b128 v[174:177], v162 offset:32768
	ds_read_b128 v[178:181], v162 offset:34816
	ds_read_b128 v[182:185], v162 offset:36864
	ds_read_b128 v[186:189], v162 offset:38912
	ds_read_b128 v[214:217], v170
	ds_read_b128 v[218:221], v171
	ds_read_b128 v[222:225], v163
	s_cmp_gt_u32 s23, 13
	s_cbranch_scc1 .Lg1_nostage0
	s_add_u32 m0, s24, 0x0
	v_mfma_f32_16x16x32_bf16 v[60:63], v[230:233], v[190:193], v[60:63]
	global_load_lds_dwordx4 v246, s[98:99]
	s_add_u32 m0, s24, 0x2000
	v_mfma_f32_16x16x32_bf16 v[56:59], v[230:233], v[194:197], v[56:59]
	global_load_lds_dwordx4 v247, s[98:99]
	v_mfma_f32_16x16x32_bf16 v[52:55], v[230:233], v[198:201], v[52:55]
	v_mfma_f32_16x16x32_bf16 v[48:51], v[230:233], v[210:213], v[48:51]
	s_add_u32 m0, s24, 0x4000
	v_mfma_f32_16x16x32_bf16 v[44:47], v[234:237], v[190:193], v[44:47]
	global_load_lds_dwordx4 v248, s[98:99]
	s_add_u32 m0, s24, 0x6000
	v_mfma_f32_16x16x32_bf16 v[40:43], v[234:237], v[194:197], v[40:43]
	global_load_lds_dwordx4 v249, s[98:99]
	v_mfma_f32_16x16x32_bf16 v[36:39], v[234:237], v[198:201], v[36:39]
	v_mfma_f32_16x16x32_bf16 v[32:35], v[234:237], v[210:213], v[32:35]
	s_add_u32 m0, s24, 0x8000
	v_mfma_f32_16x16x32_bf16 v[28:31], v[238:241], v[190:193], v[28:31]
	global_load_lds_dwordx4 v246, s[100:101]
	s_add_u32 m0, s24, 0xa000
	v_mfma_f32_16x16x32_bf16 v[24:27], v[238:241], v[194:197], v[24:27]
	global_load_lds_dwordx4 v247, s[100:101]
	v_mfma_f32_16x16x32_bf16 v[20:23], v[238:241], v[198:201], v[20:23]
	v_mfma_f32_16x16x32_bf16 v[16:19], v[238:241], v[210:213], v[16:19]
	s_add_u32 m0, s24, 0xc000
	v_mfma_f32_16x16x32_bf16 v[12:15], v[242:245], v[190:193], v[12:15]
	global_load_lds_dwordx4 v248, s[100:101]
	s_add_u32 m0, s24, 0xe000
	v_mfma_f32_16x16x32_bf16 v[8:11], v[242:245], v[194:197], v[8:11]
	global_load_lds_dwordx4 v249, s[100:101]
	v_mfma_f32_16x16x32_bf16 v[4:7], v[242:245], v[198:201], v[4:7]
	v_mfma_f32_16x16x32_bf16 v[0:3], v[242:245], v[210:213], v[0:3]
	s_add_u32 s98, s98, 0x80
	s_addc_u32 s99, s99, 0
	s_add_u32 s100, s100, 0x80
	s_addc_u32 s101, s101, 0
	s_branch .Lg1_half1

.Lg1_half1:
	ds_read_b128 v[226:229], v164
	ds_read_b128 v[230:233], v165
	ds_read_b128 v[234:237], v166
	s_waitcnt lgkmcnt(5)
	v_mfma_f32_16x16x32_bf16 v[124:127], v[214:217], v[174:177], v[124:127]
	v_mfma_f32_16x16x32_bf16 v[120:123], v[214:217], v[178:181], v[120:123]
	v_mfma_f32_16x16x32_bf16 v[116:119], v[214:217], v[182:185], v[116:119]
	v_mfma_f32_16x16x32_bf16 v[112:115], v[214:217], v[186:189], v[112:115]
	ds_read_b128 v[238:241], v167
	s_waitcnt lgkmcnt(5)
	v_mfma_f32_16x16x32_bf16 v[108:111], v[218:221], v[174:177], v[108:111]
	v_mfma_f32_16x16x32_bf16 v[104:107], v[218:221], v[178:181], v[104:107]
	v_mfma_f32_16x16x32_bf16 v[100:103], v[218:221], v[182:185], v[100:103]
	v_mfma_f32_16x16x32_bf16 v[96:99], v[218:221], v[186:189], v[96:99]
	ds_read_b128 v[242:245], v168
	ds_read_b128 v[190:193], v162 offset:33792
	s_waitcnt lgkmcnt(6)
	v_mfma_f32_16x16x32_bf16 v[92:95], v[222:225], v[174:177], v[92:95]
	v_mfma_f32_16x16x32_bf16 v[88:91], v[222:225], v[178:181], v[88:91]
	v_mfma_f32_16x16x32_bf16 v[84:87], v[222:225], v[182:185], v[84:87]
	v_mfma_f32_16x16x32_bf16 v[80:83], v[222:225], v[186:189], v[80:83]
	ds_read_b128 v[214:217], v170 offset:1024
	ds_read_b128 v[194:197], v162 offset:35840
	s_waitcnt lgkmcnt(7)
	v_mfma_f32_16x16x32_bf16 v[76:79], v[226:229], v[174:177], v[76:79]
	v_mfma_f32_16x16x32_bf16 v[72:75], v[226:229], v[178:181], v[72:75]
	v_mfma_f32_16x16x32_bf16 v[68:71], v[226:229], v[182:185], v[68:71]
	v_mfma_f32_16x16x32_bf16 v[64:67], v[226:229], v[186:189], v[64:67]
	ds_read_b128 v[218:221], v171 offset:1024
	ds_read_b128 v[198:201], v162 offset:37888
	s_waitcnt lgkmcnt(8)
	v_mfma_f32_16x16x32_bf16 v[60:63], v[230:233], v[174:177], v[60:63]
	v_mfma_f32_16x16x32_bf16 v[56:59], v[230:233], v[178:181], v[56:59]
	v_mfma_f32_16x16x32_bf16 v[52:55], v[230:233], v[182:185], v[52:55]
	v_mfma_f32_16x16x32_bf16 v[48:51], v[230:233], v[186:189], v[48:51]
	ds_read_b128 v[222:225], v163 offset:1024
	ds_read_b128 v[210:213], v162 offset:39936
	s_waitcnt lgkmcnt(9)
	v_mfma_f32_16x16x32_bf16 v[44:47], v[234:237], v[174:177], v[44:47]
	v_mfma_f32_16x16x32_bf16 v[40:43], v[234:237], v[178:181], v[40:43]
	v_mfma_f32_16x16x32_bf16 v[36:39], v[234:237], v[182:185], v[36:39]
	v_mfma_f32_16x16x32_bf16 v[32:35], v[234:237], v[186:189], v[32:35]
	ds_read_b128 v[226:229], v164 offset:1024
	s_waitcnt lgkmcnt(9)
	v_mfma_f32_16x16x32_bf16 v[28:31], v[238:241], v[174:177], v[28:31]
	v_mfma_f32_16x16x32_bf16 v[24:27], v[238:241], v[178:181], v[24:27]
	v_mfma_f32_16x16x32_bf16 v[20:23], v[238:241], v[182:185], v[20:23]
	v_mfma_f32_16x16x32_bf16 v[16:19], v[238:241], v[186:189], v[16:19]
	ds_read_b128 v[230:233], v165 offset:1024
	s_waitcnt lgkmcnt(9)
	v_mfma_f32_16x16x32_bf16 v[12:15], v[242:245], v[174:177], v[12:15]
	v_mfma_f32_16x16x32_bf16 v[8:11], v[242:245], v[178:181], v[8:11]
	v_mfma_f32_16x16x32_bf16 v[4:7], v[242:245], v[182:185], v[4:7]
	v_mfma_f32_16x16x32_bf16 v[0:3], v[242:245], v[186:189], v[0:3]
	ds_read_b128 v[234:237], v166 offset:1024
	s_waitcnt lgkmcnt(3)
	v_mfma_f32_16x16x32_bf16 v[124:127], v[214:217], v[190:193], v[124:127]
	v_mfma_f32_16x16x32_bf16 v[120:123], v[214:217], v[194:197], v[120:123]
	v_mfma_f32_16x16x32_bf16 v[116:119], v[214:217], v[198:201], v[116:119]
	v_mfma_f32_16x16x32_bf16 v[112:115], v[214:217], v[210:213], v[112:115]
	ds_read_b128 v[238:241], v167 offset:1024
	v_mfma_f32_16x16x32_bf16 v[108:111], v[218:221], v[190:193], v[108:111]
	v_mfma_f32_16x16x32_bf16 v[104:107], v[218:221], v[194:197], v[104:107]
	v_mfma_f32_16x16x32_bf16 v[100:103], v[218:221], v[198:201], v[100:103]
	v_mfma_f32_16x16x32_bf16 v[96:99], v[218:221], v[210:213], v[96:99]
	ds_read_b128 v[242:245], v168 offset:1024
	v_mfma_f32_16x16x32_bf16 v[92:95], v[222:225], v[190:193], v[92:95]
	v_mfma_f32_16x16x32_bf16 v[88:91], v[222:225], v[194:197], v[88:91]
	v_mfma_f32_16x16x32_bf16 v[84:87], v[222:225], v[198:201], v[84:87]
	v_mfma_f32_16x16x32_bf16 v[80:83], v[222:225], v[210:213], v[80:83]
	s_waitcnt lgkmcnt(4)
	v_mfma_f32_16x16x32_bf16 v[76:79], v[226:229], v[190:193], v[76:79]
	v_mfma_f32_16x16x32_bf16 v[72:75], v[226:229], v[194:197], v[72:75]
	v_mfma_f32_16x16x32_bf16 v[68:71], v[226:229], v[198:201], v[68:71]
	v_mfma_f32_16x16x32_bf16 v[64:67], v[226:229], v[210:213], v[64:67]
	s_waitcnt lgkmcnt(0)
	s_waitcnt vmcnt(0)
	s_barrier
	s_cmp_gt_u32 s23, 13
	s_cbranch_scc1 .Lg1_last
	ds_read_b128 v[174:177], v153 offset:32768
	ds_read_b128 v[178:181], v153 offset:34816
	ds_read_b128 v[182:185], v153 offset:36864
	ds_read_b128 v[186:189], v153 offset:38912
	ds_read_b128 v[214:217], v154
	ds_read_b128 v[218:221], v155
	ds_read_b128 v[222:225], v156
	s_add_u32 m0, s24, 0x10400
	v_mfma_f32_16x16x32_bf16 v[60:63], v[230:233], v[190:193], v[60:63]
	global_load_lds_dwordx4 v246, s[98:99]
	s_add_u32 m0, s24, 0x12400
	v_mfma_f32_16x16x32_bf16 v[56:59], v[230:233], v[194:197], v[56:59]
	global_load_lds_dwordx4 v247, s[98:99]
	v_mfma_f32_16x16x32_bf16 v[52:55], v[230:233], v[198:201], v[52:55]
	v_mfma_f32_16x16x32_bf16 v[48:51], v[230:233], v[210:213], v[48:51]
	s_add_u32 m0, s24, 0x14400
	v_mfma_f32_16x16x32_bf16 v[44:47], v[234:237], v[190:193], v[44:47]
	global_load_lds_dwordx4 v248, s[98:99]
	s_add_u32 m0, s24, 0x16400
	v_mfma_f32_16x16x32_bf16 v[40:43], v[234:237], v[194:197], v[40:43]
	global_load_lds_dwordx4 v249, s[98:99]
	v_mfma_f32_16x16x32_bf16 v[36:39], v[234:237], v[198:201], v[36:39]
	v_mfma_f32_16x16x32_bf16 v[32:35], v[234:237], v[210:213], v[32:35]
	s_add_u32 m0, s24, 0x18400
	v_mfma_f32_16x16x32_bf16 v[28:31], v[238:241], v[190:193], v[28:31]
	global_load_lds_dwordx4 v246, s[100:101]
	s_add_u32 m0, s24, 0x1a400
	v_mfma_f32_16x16x32_bf16 v[24:27], v[238:241], v[194:197], v[24:27]
	global_load_lds_dwordx4 v247, s[100:101]
	v_mfma_f32_16x16x32_bf16 v[20:23], v[238:241], v[198:201], v[20:23]
	v_mfma_f32_16x16x32_bf16 v[16:19], v[238:241], v[210:213], v[16:19]
	s_add_u32 m0, s24, 0x1c400
	v_mfma_f32_16x16x32_bf16 v[12:15], v[242:245], v[190:193], v[12:15]
	global_load_lds_dwordx4 v248, s[100:101]
	s_add_u32 m0, s24, 0x1e400
	v_mfma_f32_16x16x32_bf16 v[8:11], v[242:245], v[194:197], v[8:11]
	global_load_lds_dwordx4 v249, s[100:101]
	v_mfma_f32_16x16x32_bf16 v[4:7], v[242:245], v[198:201], v[4:7]
	v_mfma_f32_16x16x32_bf16 v[0:3], v[242:245], v[210:213], v[0:3]
	s_add_u32 s98, s98, 0x80
	s_addc_u32 s99, s99, 0
	s_add_u32 s100, s100, 0x80
	s_addc_u32 s101, s101, 0
	s_add_i32 s23, s23, 2
	s_branch .LBB0_203

.LBB0_1788:
	ds_read_b128 v[222:225], v159
	ds_read_b128 v[226:229], v160
	ds_read_b128 v[230:233], v161
	s_waitcnt lgkmcnt(5)
	v_mfma_f32_16x16x32_bf16 v[124:127], v[210:213], v[178:181], v[124:127]
	v_mfma_f32_16x16x32_bf16 v[120:123], v[210:213], v[182:185], v[120:123]
	v_mfma_f32_16x16x32_bf16 v[116:119], v[210:213], v[186:189], v[116:119]
	v_mfma_f32_16x16x32_bf16 v[112:115], v[210:213], v[190:193], v[112:115]
	ds_read_b128 v[234:237], v162
	s_waitcnt lgkmcnt(5)
	v_mfma_f32_16x16x32_bf16 v[108:111], v[214:217], v[178:181], v[108:111]
	v_mfma_f32_16x16x32_bf16 v[104:107], v[214:217], v[182:185], v[104:107]
	v_mfma_f32_16x16x32_bf16 v[100:103], v[214:217], v[186:189], v[100:103]
	v_mfma_f32_16x16x32_bf16 v[96:99], v[214:217], v[190:193], v[96:99]
	ds_read_b128 v[238:241], v163
	ds_read_b128 v[194:197], v155 offset:33792
	s_waitcnt lgkmcnt(6)
	v_mfma_f32_16x16x32_bf16 v[92:95], v[218:221], v[178:181], v[92:95]
	v_mfma_f32_16x16x32_bf16 v[88:91], v[218:221], v[182:185], v[88:91]
	v_mfma_f32_16x16x32_bf16 v[84:87], v[218:221], v[186:189], v[84:87]
	v_mfma_f32_16x16x32_bf16 v[80:83], v[218:221], v[190:193], v[80:83]
	ds_read_b128 v[210:213], v156 offset:1024
	ds_read_b128 v[198:201], v155 offset:35840
	s_waitcnt lgkmcnt(7)
	v_mfma_f32_16x16x32_bf16 v[76:79], v[222:225], v[178:181], v[76:79]
	v_mfma_f32_16x16x32_bf16 v[72:75], v[222:225], v[182:185], v[72:75]
	v_mfma_f32_16x16x32_bf16 v[68:71], v[222:225], v[186:189], v[68:71]
	v_mfma_f32_16x16x32_bf16 v[64:67], v[222:225], v[190:193], v[64:67]
	ds_read_b128 v[214:217], v157 offset:1024
	ds_read_b128 v[202:205], v155 offset:37888
	s_waitcnt lgkmcnt(8)
	v_mfma_f32_16x16x32_bf16 v[60:63], v[226:229], v[178:181], v[60:63]
	v_mfma_f32_16x16x32_bf16 v[56:59], v[226:229], v[182:185], v[56:59]
	v_mfma_f32_16x16x32_bf16 v[52:55], v[226:229], v[186:189], v[52:55]
	v_mfma_f32_16x16x32_bf16 v[48:51], v[226:229], v[190:193], v[48:51]
	ds_read_b128 v[218:221], v158 offset:1024
	ds_read_b128 v[206:209], v155 offset:39936
	s_waitcnt lgkmcnt(9)
	v_mfma_f32_16x16x32_bf16 v[44:47], v[230:233], v[178:181], v[44:47]
	v_mfma_f32_16x16x32_bf16 v[40:43], v[230:233], v[182:185], v[40:43]
	v_mfma_f32_16x16x32_bf16 v[36:39], v[230:233], v[186:189], v[36:39]
	v_mfma_f32_16x16x32_bf16 v[32:35], v[230:233], v[190:193], v[32:35]
	ds_read_b128 v[222:225], v159 offset:1024
	s_waitcnt lgkmcnt(9)
	v_mfma_f32_16x16x32_bf16 v[28:31], v[234:237], v[178:181], v[28:31]
	v_mfma_f32_16x16x32_bf16 v[24:27], v[234:237], v[182:185], v[24:27]
	v_mfma_f32_16x16x32_bf16 v[20:23], v[234:237], v[186:189], v[20:23]
	v_mfma_f32_16x16x32_bf16 v[16:19], v[234:237], v[190:193], v[16:19]
	ds_read_b128 v[226:229], v160 offset:1024
	s_waitcnt lgkmcnt(9)
	v_mfma_f32_16x16x32_bf16 v[12:15], v[238:241], v[178:181], v[12:15]
	v_mfma_f32_16x16x32_bf16 v[8:11], v[238:241], v[182:185], v[8:11]
	v_mfma_f32_16x16x32_bf16 v[4:7], v[238:241], v[186:189], v[4:7]
	v_mfma_f32_16x16x32_bf16 v[0:3], v[238:241], v[190:193], v[0:3]
	ds_read_b128 v[230:233], v161 offset:1024
	s_waitcnt lgkmcnt(3)
	v_mfma_f32_16x16x32_bf16 v[124:127], v[210:213], v[194:197], v[124:127]
	v_mfma_f32_16x16x32_bf16 v[120:123], v[210:213], v[198:201], v[120:123]
	v_mfma_f32_16x16x32_bf16 v[116:119], v[210:213], v[202:205], v[116:119]
	v_mfma_f32_16x16x32_bf16 v[112:115], v[210:213], v[206:209], v[112:115]
	ds_read_b128 v[234:237], v162 offset:1024
	v_mfma_f32_16x16x32_bf16 v[108:111], v[214:217], v[194:197], v[108:111]
	v_mfma_f32_16x16x32_bf16 v[104:107], v[214:217], v[198:201], v[104:107]
	v_mfma_f32_16x16x32_bf16 v[100:103], v[214:217], v[202:205], v[100:103]
	v_mfma_f32_16x16x32_bf16 v[96:99], v[214:217], v[206:209], v[96:99]
	ds_read_b128 v[238:241], v163 offset:1024
	v_mfma_f32_16x16x32_bf16 v[92:95], v[218:221], v[194:197], v[92:95]
	v_mfma_f32_16x16x32_bf16 v[88:91], v[218:221], v[198:201], v[88:91]
	v_mfma_f32_16x16x32_bf16 v[84:87], v[218:221], v[202:205], v[84:87]
	v_mfma_f32_16x16x32_bf16 v[80:83], v[218:221], v[206:209], v[80:83]
	s_waitcnt lgkmcnt(4)
	v_mfma_f32_16x16x32_bf16 v[76:79], v[222:225], v[194:197], v[76:79]
	v_mfma_f32_16x16x32_bf16 v[72:75], v[222:225], v[198:201], v[72:75]
	v_mfma_f32_16x16x32_bf16 v[68:71], v[222:225], v[202:205], v[68:71]
	v_mfma_f32_16x16x32_bf16 v[64:67], v[222:225], v[206:209], v[64:67]
	s_waitcnt lgkmcnt(0)
	s_waitcnt vmcnt(0)
	s_barrier
	ds_read_b128 v[178:181], v164 offset:32768
	ds_read_b128 v[182:185], v164 offset:34816
	ds_read_b128 v[186:189], v164 offset:36864
	ds_read_b128 v[190:193], v164 offset:38912
	ds_read_b128 v[210:213], v172
	ds_read_b128 v[214:217], v173
	ds_read_b128 v[218:221], v165
	s_cmp_gt_u32 s1, 13
	s_cbranch_scc1 .Lg4_nostage0
	s_add_u32 m0, s45, 0x0
	v_mfma_f32_16x16x32_bf16 v[60:63], v[226:229], v[194:197], v[60:63]
	global_load_lds_dwordx4 v174, s[98:99]
	s_add_u32 m0, s45, 0x2000
	v_mfma_f32_16x16x32_bf16 v[56:59], v[226:229], v[198:201], v[56:59]
	global_load_lds_dwordx4 v175, s[98:99]
	v_mfma_f32_16x16x32_bf16 v[52:55], v[226:229], v[202:205], v[52:55]
	v_mfma_f32_16x16x32_bf16 v[48:51], v[226:229], v[206:209], v[48:51]
	s_add_u32 m0, s45, 0x4000
	v_mfma_f32_16x16x32_bf16 v[44:47], v[230:233], v[194:197], v[44:47]
	global_load_lds_dwordx4 v176, s[98:99]
	s_add_u32 m0, s45, 0x6000
	v_mfma_f32_16x16x32_bf16 v[40:43], v[230:233], v[198:201], v[40:43]
	global_load_lds_dwordx4 v177, s[98:99]
	v_mfma_f32_16x16x32_bf16 v[36:39], v[230:233], v[202:205], v[36:39]
	v_mfma_f32_16x16x32_bf16 v[32:35], v[230:233], v[206:209], v[32:35]
	s_add_u32 m0, s45, 0x8000
	v_mfma_f32_16x16x32_bf16 v[28:31], v[234:237], v[194:197], v[28:31]
	global_load_lds_dwordx4 v174, s[100:101]
	s_add_u32 m0, s45, 0xa000
	v_mfma_f32_16x16x32_bf16 v[24:27], v[234:237], v[198:201], v[24:27]
	global_load_lds_dwordx4 v175, s[100:101]
	v_mfma_f32_16x16x32_bf16 v[20:23], v[234:237], v[202:205], v[20:23]
	v_mfma_f32_16x16x32_bf16 v[16:19], v[234:237], v[206:209], v[16:19]
	s_add_u32 m0, s45, 0xc000
	v_mfma_f32_16x16x32_bf16 v[12:15], v[238:241], v[194:197], v[12:15]
	global_load_lds_dwordx4 v176, s[100:101]
	s_add_u32 m0, s45, 0xe000
	v_mfma_f32_16x16x32_bf16 v[8:11], v[238:241], v[198:201], v[8:11]
	global_load_lds_dwordx4 v177, s[100:101]
	v_mfma_f32_16x16x32_bf16 v[4:7], v[238:241], v[202:205], v[4:7]
	v_mfma_f32_16x16x32_bf16 v[0:3], v[238:241], v[206:209], v[0:3]
	s_add_u32 s98, s98, 0x80
	s_addc_u32 s99, s99, 0
	s_add_u32 s100, s100, 0x80
	s_addc_u32 s101, s101, 0
	s_branch .Lg4_half1

.Lg4_half1:
	ds_read_b128 v[222:225], v166
	ds_read_b128 v[226:229], v167
	ds_read_b128 v[230:233], v168
	s_waitcnt lgkmcnt(5)
	v_mfma_f32_16x16x32_bf16 v[124:127], v[210:213], v[178:181], v[124:127]
	v_mfma_f32_16x16x32_bf16 v[120:123], v[210:213], v[182:185], v[120:123]
	v_mfma_f32_16x16x32_bf16 v[116:119], v[210:213], v[186:189], v[116:119]
	v_mfma_f32_16x16x32_bf16 v[112:115], v[210:213], v[190:193], v[112:115]
	ds_read_b128 v[234:237], v169
	s_waitcnt lgkmcnt(5)
	v_mfma_f32_16x16x32_bf16 v[108:111], v[214:217], v[178:181], v[108:111]
	v_mfma_f32_16x16x32_bf16 v[104:107], v[214:217], v[182:185], v[104:107]
	v_mfma_f32_16x16x32_bf16 v[100:103], v[214:217], v[186:189], v[100:103]
	v_mfma_f32_16x16x32_bf16 v[96:99], v[214:217], v[190:193], v[96:99]
	ds_read_b128 v[238:241], v170
	ds_read_b128 v[194:197], v164 offset:33792
	s_waitcnt lgkmcnt(6)
	v_mfma_f32_16x16x32_bf16 v[92:95], v[218:221], v[178:181], v[92:95]
	v_mfma_f32_16x16x32_bf16 v[88:91], v[218:221], v[182:185], v[88:91]
	v_mfma_f32_16x16x32_bf16 v[84:87], v[218:221], v[186:189], v[84:87]
	v_mfma_f32_16x16x32_bf16 v[80:83], v[218:221], v[190:193], v[80:83]
	ds_read_b128 v[210:213], v172 offset:1024
	ds_read_b128 v[198:201], v164 offset:35840
	s_waitcnt lgkmcnt(7)
	v_mfma_f32_16x16x32_bf16 v[76:79], v[222:225], v[178:181], v[76:79]
	v_mfma_f32_16x16x32_bf16 v[72:75], v[222:225], v[182:185], v[72:75]
	v_mfma_f32_16x16x32_bf16 v[68:71], v[222:225], v[186:189], v[68:71]
	v_mfma_f32_16x16x32_bf16 v[64:67], v[222:225], v[190:193], v[64:67]
	ds_read_b128 v[214:217], v173 offset:1024
	ds_read_b128 v[202:205], v164 offset:37888
	s_waitcnt lgkmcnt(8)
	v_mfma_f32_16x16x32_bf16 v[60:63], v[226:229], v[178:181], v[60:63]
	v_mfma_f32_16x16x32_bf16 v[56:59], v[226:229], v[182:185], v[56:59]
	v_mfma_f32_16x16x32_bf16 v[52:55], v[226:229], v[186:189], v[52:55]
	v_mfma_f32_16x16x32_bf16 v[48:51], v[226:229], v[190:193], v[48:51]
	ds_read_b128 v[218:221], v165 offset:1024
	ds_read_b128 v[206:209], v164 offset:39936
	s_waitcnt lgkmcnt(9)
	v_mfma_f32_16x16x32_bf16 v[44:47], v[230:233], v[178:181], v[44:47]
	v_mfma_f32_16x16x32_bf16 v[40:43], v[230:233], v[182:185], v[40:43]
	v_mfma_f32_16x16x32_bf16 v[36:39], v[230:233], v[186:189], v[36:39]
	v_mfma_f32_16x16x32_bf16 v[32:35], v[230:233], v[190:193], v[32:35]
	ds_read_b128 v[222:225], v166 offset:1024
	s_waitcnt lgkmcnt(9)
	v_mfma_f32_16x16x32_bf16 v[28:31], v[234:237], v[178:181], v[28:31]
	v_mfma_f32_16x16x32_bf16 v[24:27], v[234:237], v[182:185], v[24:27]
	v_mfma_f32_16x16x32_bf16 v[20:23], v[234:237], v[186:189], v[20:23]
	v_mfma_f32_16x16x32_bf16 v[16:19], v[234:237], v[190:193], v[16:19]
	ds_read_b128 v[226:229], v167 offset:1024
	s_waitcnt lgkmcnt(9)
	v_mfma_f32_16x16x32_bf16 v[12:15], v[238:241], v[178:181], v[12:15]
	v_mfma_f32_16x16x32_bf16 v[8:11], v[238:241], v[182:185], v[8:11]
	v_mfma_f32_16x16x32_bf16 v[4:7], v[238:241], v[186:189], v[4:7]
	v_mfma_f32_16x16x32_bf16 v[0:3], v[238:241], v[190:193], v[0:3]
	ds_read_b128 v[230:233], v168 offset:1024
	s_waitcnt lgkmcnt(3)
	v_mfma_f32_16x16x32_bf16 v[124:127], v[210:213], v[194:197], v[124:127]
	v_mfma_f32_16x16x32_bf16 v[120:123], v[210:213], v[198:201], v[120:123]
	v_mfma_f32_16x16x32_bf16 v[116:119], v[210:213], v[202:205], v[116:119]
	v_mfma_f32_16x16x32_bf16 v[112:115], v[210:213], v[206:209], v[112:115]
	ds_read_b128 v[234:237], v169 offset:1024
	v_mfma_f32_16x16x32_bf16 v[108:111], v[214:217], v[194:197], v[108:111]
	v_mfma_f32_16x16x32_bf16 v[104:107], v[214:217], v[198:201], v[104:107]
	v_mfma_f32_16x16x32_bf16 v[100:103], v[214:217], v[202:205], v[100:103]
	v_mfma_f32_16x16x32_bf16 v[96:99], v[214:217], v[206:209], v[96:99]
	ds_read_b128 v[238:241], v170 offset:1024
	v_mfma_f32_16x16x32_bf16 v[92:95], v[218:221], v[194:197], v[92:95]
	v_mfma_f32_16x16x32_bf16 v[88:91], v[218:221], v[198:201], v[88:91]
	v_mfma_f32_16x16x32_bf16 v[84:87], v[218:221], v[202:205], v[84:87]
	v_mfma_f32_16x16x32_bf16 v[80:83], v[218:221], v[206:209], v[80:83]
	s_waitcnt lgkmcnt(4)
	v_mfma_f32_16x16x32_bf16 v[76:79], v[222:225], v[194:197], v[76:79]
	v_mfma_f32_16x16x32_bf16 v[72:75], v[222:225], v[198:201], v[72:75]
	v_mfma_f32_16x16x32_bf16 v[68:71], v[222:225], v[202:205], v[68:71]
	v_mfma_f32_16x16x32_bf16 v[64:67], v[222:225], v[206:209], v[64:67]
	s_waitcnt lgkmcnt(0)
	s_waitcnt vmcnt(0)
	s_barrier
	s_cmp_gt_u32 s1, 13
	s_cbranch_scc1 .Lg4_last
	ds_read_b128 v[178:181], v155 offset:32768
	ds_read_b128 v[182:185], v155 offset:34816
	ds_read_b128 v[186:189], v155 offset:36864
	ds_read_b128 v[190:193], v155 offset:38912
	ds_read_b128 v[210:213], v156
	ds_read_b128 v[214:217], v157
	ds_read_b128 v[218:221], v158
	s_add_u32 m0, s45, 0x10400
	v_mfma_f32_16x16x32_bf16 v[60:63], v[226:229], v[194:197], v[60:63]
	global_load_lds_dwordx4 v174, s[98:99]
	s_add_u32 m0, s45, 0x12400
	v_mfma_f32_16x16x32_bf16 v[56:59], v[226:229], v[198:201], v[56:59]
	global_load_lds_dwordx4 v175, s[98:99]
	v_mfma_f32_16x16x32_bf16 v[52:55], v[226:229], v[202:205], v[52:55]
	v_mfma_f32_16x16x32_bf16 v[48:51], v[226:229], v[206:209], v[48:51]
	s_add_u32 m0, s45, 0x14400
	v_mfma_f32_16x16x32_bf16 v[44:47], v[230:233], v[194:197], v[44:47]
	global_load_lds_dwordx4 v176, s[98:99]
	s_add_u32 m0, s45, 0x16400
	v_mfma_f32_16x16x32_bf16 v[40:43], v[230:233], v[198:201], v[40:43]
	global_load_lds_dwordx4 v177, s[98:99]
	v_mfma_f32_16x16x32_bf16 v[36:39], v[230:233], v[202:205], v[36:39]
	v_mfma_f32_16x16x32_bf16 v[32:35], v[230:233], v[206:209], v[32:35]
	s_add_u32 m0, s45, 0x18400
	v_mfma_f32_16x16x32_bf16 v[28:31], v[234:237], v[194:197], v[28:31]
	global_load_lds_dwordx4 v174, s[100:101]
	s_add_u32 m0, s45, 0x1a400
	v_mfma_f32_16x16x32_bf16 v[24:27], v[234:237], v[198:201], v[24:27]
	global_load_lds_dwordx4 v175, s[100:101]
	v_mfma_f32_16x16x32_bf16 v[20:23], v[234:237], v[202:205], v[20:23]
	v_mfma_f32_16x16x32_bf16 v[16:19], v[234:237], v[206:209], v[16:19]
	s_add_u32 m0, s45, 0x1c400
	v_mfma_f32_16x16x32_bf16 v[12:15], v[238:241], v[194:197], v[12:15]
	global_load_lds_dwordx4 v176, s[100:101]
	s_add_u32 m0, s45, 0x1e400
	v_mfma_f32_16x16x32_bf16 v[8:11], v[238:241], v[198:201], v[8:11]
	global_load_lds_dwordx4 v177, s[100:101]
	v_mfma_f32_16x16x32_bf16 v[4:7], v[238:241], v[202:205], v[4:7]
	v_mfma_f32_16x16x32_bf16 v[0:3], v[238:241], v[206:209], v[0:3]
	s_add_u32 s98, s98, 0x80
	s_addc_u32 s99, s99, 0
	s_add_u32 s100, s100, 0x80
	s_addc_u32 s101, s101, 0
	s_add_i32 s1, s1, 2
	s_branch .LBB0_1788
